# h3 items: single all-states-done wait + acquire per workgroup
# speedup vs baseline: 1.0122x; 1.0122x over previous
.LBB0_571:
	v_lshl_add_u64 v[2:3], s[62:63], 0, v[50:51]
	v_lshl_add_u64 v[6:7], s[62:63], 0, v[56:57]
	v_lshl_add_u64 v[8:9], s[62:63], 0, v[60:61]
	v_lshl_add_u64 v[104:105], s[62:63], 0, v[62:63]
	v_lshl_add_u64 v[22:23], s[62:63], 0, v[80:81]
	v_lshl_add_u64 v[32:33], s[62:63], 0, v[38:39]
	v_lshl_add_u64 v[4:5], s[62:63], 0, v[58:59]
	v_lshl_add_u64 v[106:107], s[62:63], 0, v[66:67]
	v_lshl_add_u64 v[110:111], s[62:63], 0, v[68:69]
	v_lshl_add_u64 v[112:113], s[62:63], 0, v[70:71]
	v_lshl_add_u64 v[116:117], s[62:63], 0, v[72:73]
	v_lshl_add_u64 v[114:115], s[62:63], 0, v[74:75]
	v_lshl_add_u64 v[118:119], s[62:63], 0, v[76:77]
	v_lshl_add_u64 v[108:109], s[62:63], 0, v[78:79]
	v_lshl_add_u64 v[14:15], s[62:63], 0, v[42:43]
	v_lshl_add_u64 v[24:25], s[62:63], 0, v[82:83]
	v_lshl_add_u64 v[28:29], s[62:63], 0, v[84:85]
	v_lshl_add_u64 v[98:99], s[62:63], 0, v[86:87]
	v_lshl_add_u64 v[12:13], s[62:63], 0, v[88:89]
	v_lshl_add_u64 v[18:19], s[62:63], 0, v[90:91]
	v_lshl_add_u64 v[10:11], s[62:63], 0, v[92:93]
	v_lshl_add_u64 v[16:17], s[62:63], 0, v[54:55]
	v_lshl_add_u64 v[20:21], s[62:63], 0, v[52:53]
	v_lshl_add_u64 v[26:27], s[62:63], 0, v[48:49]
	v_lshl_add_u64 v[96:97], s[62:63], 0, v[46:47]
	v_lshl_add_u64 v[100:101], s[62:63], 0, v[44:45]
	v_lshl_add_u64 v[30:31], s[62:63], 0, v[40:41]
	global_load_ushort v138, v[104:105], off
	global_load_ushort v142, v[106:107], off
	global_load_ushort v143, v[110:111], off
	global_load_ushort v139, v[112:113], off
	global_load_ushort v157, v[116:117], off
	global_load_ushort v140, v[114:115], off
	global_load_ushort v162, v[118:119], off
	global_load_ushort v141, v[108:109], off
	global_load_ushort v163, v[2:3], off offset:-2048
	global_load_ushort v164, v[2:3], off offset:-1024
	global_load_ushort v165, v[2:3], off
	global_load_ushort v166, v[2:3], off offset:1024
	global_load_ushort v167, v[6:7], off
	s_nop 0
	global_load_ushort v6, v[4:5], off
	global_load_ushort v7, v[8:9], off
	global_load_ushort v168, v[2:3], off offset:-1984
	global_load_ushort v169, v[22:23], off
	global_load_ushort v170, v[14:15], off offset:-1024
	global_load_ushort v171, v[14:15], off
	s_nop 0
	global_load_ushort v22, v[14:15], off offset:1024
	global_load_ushort v23, v[24:25], off
	global_load_ushort v172, v[28:29], off
	global_load_ushort v8, v[98:99], off
	global_load_ushort v9, v[12:13], off
	global_load_ushort v173, v[18:19], off
	global_load_ushort v174, v[10:11], off
	global_load_ushort v175, v[16:17], off
	global_load_ushort v176, v[20:21], off
	global_load_ushort v177, v[26:27], off
	global_load_ushort v178, v[96:97], off
	global_load_ushort v179, v[100:101], off
	global_load_ushort v180, v[30:31], off
	v_add_co_u32_e32 v2, vcc, s11, v32
	v_lshl_add_u64 v[102:103], s[62:63], 0, v[36:37]
	s_nop 0
	v_addc_co_u32_e32 v3, vcc, 0, v33, vcc
	v_add_co_u32_e32 v4, vcc, s12, v102
	v_lshl_add_u64 v[126:127], s[62:63], 0, v[34:35]
	s_nop 0
	v_addc_co_u32_e32 v5, vcc, 0, v103, vcc
	v_add_co_u32_e32 v144, vcc, s14, v126
	v_cvt_pk_bf16_f32 v120, v64, v65
	s_nop 0
	v_addc_co_u32_e32 v145, vcc, 0, v127, vcc
	v_add_co_u32_e32 v146, vcc, s15, v126
	v_cvt_pk_bf16_f32 v121, v94, v95
	s_nop 0
	v_addc_co_u32_e32 v147, vcc, 0, v127, vcc
	v_add_co_u32_e32 v148, vcc, s16, v126
	s_add_i32 s10, s10, -1
	s_nop 0
	v_addc_co_u32_e32 v149, vcc, 0, v127, vcc
	v_add_co_u32_e32 v150, vcc, s17, v126
	v_lshl_add_u64 v[34:35], v[34:35], 0, s[2:3]
	s_nop 0
	v_addc_co_u32_e32 v151, vcc, 0, v127, vcc
	v_add_co_u32_e32 v152, vcc, s18, v126
	s_waitcnt vmcnt(0)
	v_perm_b32 v139, v157, v139, s13
	v_addc_co_u32_e32 v153, vcc, 0, v127, vcc
	v_add_co_u32_e32 v154, vcc, s19, v126
	v_perm_b32 v140, v162, v140, s13
	s_nop 0
	v_addc_co_u32_e32 v155, vcc, 0, v127, vcc
	v_add_co_u32_e32 v158, vcc, s20, v126
	v_lshl_add_u64 v[36:37], v[36:37], 0, s[4:5]
	s_nop 0
	v_addc_co_u32_e32 v159, vcc, 0, v127, vcc
	v_add_co_u32_e32 v160, vcc, s21, v126
	v_lshl_add_u64 v[38:39], v[38:39], 0, s[6:7]
	s_nop 0
	v_addc_co_u32_e32 v161, vcc, 0, v127, vcc
	global_load_dwordx4 v[18:21], v[2:3], off offset:1024
	global_load_dwordx4 v[96:99], v[2:3], off offset:1056
	global_load_dwordx4 v[100:103], v[4:5], off offset:1024
	global_load_dwordx4 v[104:107], v[4:5], off offset:1280
	global_load_dwordx4 v[108:111], v[4:5], off offset:1536
	global_load_dwordx4 v[112:115], v[4:5], off offset:1792
	global_load_dwordx4 v[116:119], v[4:5], off offset:2048
	global_load_dwordx4 v[126:129], v[4:5], off offset:2304
	global_load_dwordx4 v[130:133], v[4:5], off offset:2560
	global_load_dwordx4 v[134:137], v[4:5], off offset:2816
	v_perm_b32 v5, v138, v7, s13
	v_perm_b32 v4, v6, v167, s13
	v_perm_b32 v3, v166, v165, s13
	v_perm_b32 v2, v164, v163, s13
	v_perm_b32 v141, v169, v141, s13
	v_perm_b32 v138, v143, v142, s13
	v_perm_b32 v24, v172, v23, s13
	v_perm_b32 v23, v22, v171, s13
	v_perm_b32 v22, v170, v168, s13
	s_waitcnt lgkmcnt(0)
	s_barrier
	v_perm_b32 v25, v9, v8, s13
	s_waitcnt vmcnt(9)
	v_mfma_f32_32x32x16_bf16 v[2:17], v[2:5], v[18:21], 0
	v_perm_b32 v143, v180, v179, s13
	v_perm_b32 v142, v178, v177, s13
	v_lshl_add_u64 v[40:41], v[40:41], 0, s[8:9]
	v_lshl_add_u64 v[42:43], v[42:43], 0, s[8:9]
	v_lshl_add_u64 v[44:45], v[44:45], 0, s[8:9]
	v_lshl_add_u64 v[46:47], v[46:47], 0, s[8:9]
	v_lshl_add_u64 v[48:49], v[48:49], 0, s[8:9]
	v_mfma_f32_32x32x16_bf16 v[18:33], v[22:25], v[18:21], 0
	v_lshl_add_u64 v[50:51], v[50:51], 0, s[8:9]
	v_lshl_add_u64 v[52:53], v[52:53], 0, s[8:9]
	v_lshl_add_u64 v[54:55], v[54:55], 0, s[8:9]
	v_lshl_add_u64 v[56:57], v[56:57], 0, s[8:9]
	v_lshl_add_u64 v[58:59], v[58:59], 0, s[8:9]
	v_lshl_add_u64 v[60:61], v[60:61], 0, s[8:9]
	v_lshl_add_u64 v[62:63], v[62:63], 0, s[8:9]
	s_waitcnt vmcnt(8)
	v_mfma_f32_32x32x16_bf16 v[2:17], v[138:141], v[96:99], v[2:17]
	v_perm_b32 v141, v176, v175, s13
	v_perm_b32 v140, v174, v173, s13
	v_lshl_add_u64 v[66:67], v[66:67], 0, s[8:9]
	v_lshl_add_u64 v[68:69], v[68:69], 0, s[8:9]
	v_lshl_add_u64 v[70:71], v[70:71], 0, s[8:9]
	v_lshl_add_u64 v[72:73], v[72:73], 0, s[8:9]
	v_lshl_add_u64 v[74:75], v[74:75], 0, s[8:9]
	v_mfma_f32_32x32x16_bf16 v[18:33], v[140:143], v[96:99], v[18:33]
	s_nop 3
	ds_write_b128 v1, v[2:5]
	ds_write_b128 v1, v[6:9] offset:32
	ds_write_b128 v1, v[10:13] offset:64
	ds_write_b128 v1, v[14:17] offset:96
	s_nop 3
	ds_write_b128 v1, v[18:21] offset:128
	ds_write_b128 v1, v[22:25] offset:160
	ds_write_b128 v1, v[26:29] offset:192
	ds_write_b128 v1, v[30:33] offset:224
	s_waitcnt lgkmcnt(0)
	s_barrier
	global_store_dwordx2 v[144:145], v[120:121], off offset:1024
	ds_read_b128 v[2:5], v125
	ds_read_b128 v[6:9], v125 offset:8704
	ds_read_b128 v[10:13], v125 offset:17408
	ds_read_b128 v[14:17], v125 offset:26112
	ds_read_b128 v[18:21], v125 offset:34816
	ds_read_b128 v[22:25], v125 offset:43520
	ds_read_b128 v[26:29], v125 offset:52224
	ds_read_b128 v[30:33], v125 offset:60928
	s_waitcnt lgkmcnt(7)
	v_pk_add_f32 v[2:3], v[64:65], v[2:3]
	v_pk_add_f32 v[4:5], v[94:95], v[4:5]
	s_waitcnt vmcnt(8)
	v_pk_mul_f32 v[94:95], v[100:101], v[2:3]
	v_pk_mul_f32 v[64:65], v[102:103], v[4:5]
	s_waitcnt lgkmcnt(6)
	v_pk_fma_f32 v[2:3], v[100:101], v[2:3], v[6:7]
	v_pk_fma_f32 v[4:5], v[102:103], v[4:5], v[8:9]
	v_cvt_pk_bf16_f32 v6, v94, v95
	v_cvt_pk_bf16_f32 v7, v64, v65
	s_waitcnt vmcnt(7)
	v_pk_mul_f32 v[8:9], v[106:107], v[4:5]
	v_pk_mul_f32 v[64:65], v[104:105], v[2:3]
	s_waitcnt lgkmcnt(5)
	v_pk_fma_f32 v[4:5], v[106:107], v[4:5], v[12:13]
	v_pk_fma_f32 v[2:3], v[104:105], v[2:3], v[10:11]
	global_store_dwordx2 v[146:147], v[6:7], off offset:1024
	v_cvt_pk_bf16_f32 v6, v64, v65
	v_cvt_pk_bf16_f32 v7, v8, v9
	s_waitcnt vmcnt(7)
	v_pk_mul_f32 v[8:9], v[110:111], v[4:5]
	v_pk_mul_f32 v[10:11], v[108:109], v[2:3]
	s_waitcnt lgkmcnt(4)
	v_pk_fma_f32 v[4:5], v[110:111], v[4:5], v[16:17]
	v_pk_fma_f32 v[2:3], v[108:109], v[2:3], v[14:15]
	global_store_dwordx2 v[148:149], v[6:7], off offset:1024
	v_cvt_pk_bf16_f32 v6, v10, v11
	v_cvt_pk_bf16_f32 v7, v8, v9
	s_waitcnt vmcnt(7)
	v_pk_mul_f32 v[8:9], v[114:115], v[4:5]
	v_pk_mul_f32 v[10:11], v[112:113], v[2:3]
	s_waitcnt lgkmcnt(3)
	v_pk_fma_f32 v[4:5], v[114:115], v[4:5], v[20:21]
	v_pk_fma_f32 v[2:3], v[112:113], v[2:3], v[18:19]
	global_store_dwordx2 v[150:151], v[6:7], off offset:1024
	v_cvt_pk_bf16_f32 v6, v10, v11
	v_cvt_pk_bf16_f32 v7, v8, v9
	s_waitcnt vmcnt(7)
	v_pk_mul_f32 v[8:9], v[118:119], v[4:5]
	v_pk_mul_f32 v[10:11], v[116:117], v[2:3]
	s_waitcnt lgkmcnt(2)
	v_pk_fma_f32 v[4:5], v[118:119], v[4:5], v[24:25]
	v_pk_fma_f32 v[2:3], v[116:117], v[2:3], v[22:23]
	global_store_dwordx2 v[152:153], v[6:7], off offset:1024
	v_cvt_pk_bf16_f32 v6, v10, v11
	v_cvt_pk_bf16_f32 v7, v8, v9
	s_waitcnt vmcnt(7)
	v_pk_mul_f32 v[8:9], v[128:129], v[4:5]
	v_pk_mul_f32 v[10:11], v[126:127], v[2:3]
	s_waitcnt lgkmcnt(1)
	v_pk_fma_f32 v[4:5], v[128:129], v[4:5], v[28:29]
	v_pk_fma_f32 v[2:3], v[126:127], v[2:3], v[26:27]
	global_store_dwordx2 v[154:155], v[6:7], off offset:1024
	v_cvt_pk_bf16_f32 v6, v10, v11
	v_cvt_pk_bf16_f32 v7, v8, v9
	s_waitcnt vmcnt(7)
	v_pk_mul_f32 v[8:9], v[132:133], v[4:5]
	v_pk_mul_f32 v[10:11], v[130:131], v[2:3]
	s_waitcnt lgkmcnt(0)
	v_pk_fma_f32 v[4:5], v[132:133], v[4:5], v[32:33]
	v_pk_fma_f32 v[2:3], v[130:131], v[2:3], v[30:31]
	v_lshl_add_u64 v[76:77], v[76:77], 0, s[8:9]
	v_lshl_add_u64 v[78:79], v[78:79], 0, s[8:9]
	v_lshl_add_u64 v[80:81], v[80:81], 0, s[8:9]
	v_lshl_add_u64 v[82:83], v[82:83], 0, s[8:9]
	v_lshl_add_u64 v[84:85], v[84:85], 0, s[8:9]
	v_lshl_add_u64 v[86:87], v[86:87], 0, s[8:9]
	v_lshl_add_u64 v[88:89], v[88:89], 0, s[8:9]
	v_lshl_add_u64 v[90:91], v[90:91], 0, s[8:9]
	v_lshl_add_u64 v[92:93], v[92:93], 0, s[8:9]
	s_cmp_eq_u32 s10, 0
	global_store_dwordx2 v[158:159], v[6:7], off offset:1024
	v_cvt_pk_bf16_f32 v6, v10, v11
	v_cvt_pk_bf16_f32 v7, v8, v9
	s_waitcnt vmcnt(7)
	v_pk_mul_f32 v[94:95], v[136:137], v[4:5]
	v_pk_mul_f32 v[64:65], v[134:135], v[2:3]
	global_store_dwordx2 v[160:161], v[6:7], off offset:1024
	s_cbranch_scc0 .LBB0_571
	s_waitcnt vmcnt(0)
	s_barrier
	s_and_saveexec_b64 s[2:3], s[44:45]
	s_cbranch_execz .LBB0_576
	s_mov_b64 s[4:5], exec
	buffer_wbl2 sc1
	s_waitcnt vmcnt(0)
	s_waitcnt vmcnt(0)
	v_mbcnt_lo_u32_b32 v1, s4, 0
	v_mbcnt_hi_u32_b32 v1, s5, v1
	v_cmp_eq_u32_e32 vcc, 0, v1
	s_and_saveexec_b64 s[6:7], vcc
	s_cbranch_execz .LBB0_575
	s_lshl_b64 s[0:1], s[0:1], 2
	s_add_u32 s0, s46, s0
	s_addc_u32 s1, s47, s1
	s_bcnt1_i32_b64 s4, s[4:5]
	v_mov_b32_e32 v1, 0
	v_mov_b32_e32 v2, s4
	global_atomic_add v1, v2, s[0:1]
	global_atomic_add v1, v2, s[46:47] offset:256

.LBB0_588:
	s_mov_b32 s98, 0
	v_mul_u32_u24_e32 v6, 0x13b2, v0
	v_mov_b32_e32 v7, 13
	v_mul_lo_u16_sdwa v7, v6, v7 dst_sel:DWORD dst_unused:UNUSED_PAD src0_sel:WORD_1 src1_sel:DWORD
	v_sub_u16_e32 v7, v0, v7
	v_min_u16_e32 v7, 11, v7
	s_movk_i32 s36, 0x60
	v_lshlrev_b16_e32 v8, 3, v7
	v_add_u32_e32 v7, 8, v188
	v_and_b32_e32 v5, 63, v0
	v_mul_lo_u16_sdwa v6, v6, s36 dst_sel:DWORD dst_unused:UNUSED_PAD src0_sel:WORD_1 src1_sel:DWORD
	v_lshlrev_b32_e32 v9, 6, v7
	s_mov_b32 s36, 0xffff
	v_or_b32_e32 v10, v9, v5
	v_bitop3_b32 v9, v9, s36, v5 bitop3:0xc8
	v_mul_u32_u24_e32 v9, 0x4ec5, v9
	v_lshrrev_b32_e32 v9, 18, v9
	v_mul_lo_u16_e32 v11, 13, v9
	v_sub_u16_e32 v10, v10, v11
	v_mul_hi_u32_u24_e32 v163, 0xc0, v9
	v_mul_u32_u24_e32 v162, 0xc0, v9
	v_min_u16_e32 v9, 11, v10
	v_lshlrev_b16_e32 v10, 3, v9
	v_mul_u32_u24_e32 v9, 0xf0f1, v5
	v_lshrrev_b32_e32 v9, 20, v9
	v_mul_lo_u16_e32 v11, 17, v9
	v_sub_u16_e32 v11, v5, v11
	v_lshlrev_b32_e32 v246, 10, v7
	v_or_b32_e32 v7, 16, v188
	v_lshlrev_b32_e32 v164, 13, v9
	v_min_u16_e32 v9, 15, v11
	v_lshlrev_b16_e32 v12, 3, v9
	v_lshlrev_b32_e32 v9, 6, v7
	v_or_b32_e32 v11, v9, v5
	v_bitop3_b32 v9, v9, s36, v5 bitop3:0xc8
	v_mul_u32_u24_e32 v9, 0x4ec5, v9
	v_lshrrev_b32_e32 v9, 18, v9
	v_mul_lo_u16_e32 v13, 13, v9
	v_sub_u16_e32 v11, v11, v13
	v_mul_lo_u16_e32 v14, 0x60, v9
	v_min_u16_e32 v9, 11, v11
	v_add_u32_e32 v11, -2, v188
	v_lshl_or_b32 v13, v11, 6, v5
	s_mov_b32 s37, 0x78787879
	v_mul_hi_u32 v15, v13, s37
	v_lshrrev_b32_e32 v18, 3, v15
	v_lshl_add_u32 v15, v18, 4, v18
	v_mov_b32_e32 v3, 0
	v_sub_u32_e32 v13, v13, v15
	v_mov_b32_e32 v19, v3
	v_min_u32_e32 v13, 15, v13
	v_lshlrev_b64 v[166:167], 13, v[18:19]
	v_lshlrev_b32_e32 v18, 3, v13
	v_mov_b32_e32 v13, 0x6800
	v_lshl_add_u32 v11, v11, 10, v13
	v_or_b32_e32 v13, 24, v188
	v_lshlrev_b32_e32 v15, 6, v13
	v_or_b32_e32 v17, v15, v5
	v_bitop3_b32 v15, v15, s36, v5 bitop3:0xc8
	v_mul_u32_u24_e32 v15, 0x4ec5, v15
	v_lshrrev_b32_e32 v15, 18, v15
	s_add_u32 s0, s62, 0x1200000
	v_mul_lo_u16_e32 v19, 13, v15
	s_addc_u32 s1, s63, 0
	v_lshlrev_b32_e32 v4, 2, v189
	v_sub_u16_e32 v17, v17, v19
	v_or_b32_e32 v2, 2, v4
	v_mul_hi_u32_u24_e32 v169, 0xc0, v15
	v_mul_u32_u24_e32 v168, 0xc0, v15
	v_min_u16_e32 v15, 11, v17
	s_add_u32 s50, s62, 0x13800400
	v_cmp_gt_u32_e64 s[6:7], v2, v156
	v_or_b32_e32 v2, 3, v4
	v_lshlrev_b16_e32 v20, 3, v15
	v_add_u32_e32 v15, 6, v188
	s_addc_u32 s51, s63, 0
	v_cmp_gt_u32_e64 s[8:9], v2, v156
	v_or_b32_e32 v2, 8, v4
	v_lshlrev_b32_e32 v17, 6, v15
	s_add_u32 s52, s62, 0x15800400
	v_lshl_add_u64 v[26:27], v[160:161], 1, s[62:63]
	v_lshlrev_b32_e32 v28, 7, v156
	v_mov_b32_e32 v29, v3
	v_cmp_gt_u32_e64 s[10:11], v2, v156
	v_or_b32_e32 v2, 9, v4
	v_or_b32_e32 v19, v17, v5
	v_bitop3_b32 v17, v17, s36, v5 bitop3:0xc8
	s_addc_u32 s53, s63, 0
	v_lshl_add_u64 v[26:27], v[26:27], 0, v[28:29]
	s_mov_b64 s[54:55], 0xd800400
	v_cmp_gt_u32_e64 s[12:13], v2, v156
	v_or_b32_e32 v2, 10, v4
	v_mul_u32_u24_e32 v17, 0xf0f1, v17
	v_lshl_add_u64 v[178:179], v[26:27], 0, s[54:55]
	s_add_u32 s54, s62, 0xb800400
	v_writelane_b32 v254, s92, 1
	v_cmp_gt_u32_e64 s[14:15], v2, v156
	v_or_b32_e32 v2, 11, v4
	v_lshrrev_b32_e32 v17, 20, v17
	s_addc_u32 s55, s63, 0
	v_writelane_b32 v254, s90, 2
	v_cmp_gt_u32_e64 s[16:17], v2, v156
	v_or_b32_e32 v2, 16, v4
	v_mul_lo_u16_e32 v21, 17, v17
	s_add_u32 s56, s62, 0x11800400
	v_writelane_b32 v254, s91, 3
	v_cmp_gt_u32_e64 s[18:19], v2, v156
	v_or_b32_e32 v2, 17, v4
	v_sub_u16_e32 v19, v19, v21
	s_addc_u32 s57, s63, 0
	v_writelane_b32 v254, s89, 4
	v_cmp_gt_u32_e64 s[20:21], v2, v156
	v_or_b32_e32 v2, 18, v4
	v_lshlrev_b32_e32 v170, 13, v17
	v_min_u16_e32 v17, 15, v19
	v_lshlrev_b32_e32 v247, 10, v15
	v_add_u32_e32 v15, 14, v188
	s_add_u32 s87, s62, 0x1400400
	v_writelane_b32 v254, s88, 5
	v_cmp_gt_u32_e64 s[22:23], v2, v156
	v_or_b32_e32 v2, 19, v4
	v_lshlrev_b16_e32 v22, 3, v17
	v_lshlrev_b32_e32 v17, 6, v15
	s_addc_u32 s88, s63, 0
	v_cmp_gt_u32_e64 s[24:25], v2, v156
	v_or_b32_e32 v2, 24, v4
	v_or_b32_e32 v19, v17, v5
	v_bitop3_b32 v5, v17, s36, v5 bitop3:0xc8
	s_add_u32 s89, s62, 0x19800400
	v_cmp_gt_u32_e64 s[26:27], v2, v156
	v_or_b32_e32 v2, 25, v4
	v_mul_u32_u24_e32 v5, 0xf0f1, v5
	s_addc_u32 s91, s63, 0
	v_cmp_gt_u32_e64 s[28:29], v2, v156
	v_or_b32_e32 v2, 26, v4
	v_lshrrev_b32_e32 v5, 20, v5
	s_add_u32 s92, s62, 0x1c800400
	v_cmp_gt_u32_e64 s[30:31], v2, v156
	v_or_b32_e32 v2, 27, v4
	v_mul_lo_u16_e32 v17, 17, v5
	s_addc_u32 s93, s63, 0
	v_cmp_gt_u32_e64 s[34:35], v2, v156
	v_lshlrev_b32_e32 v2, 6, v156
	v_sub_u16_e32 v17, v19, v17
	s_add_u32 s66, s62, 0x9800400
	v_mov_b32_e32 v159, v3
	s_movk_i32 s42, 0x80
	v_lshlrev_b32_e32 v172, 13, v5
	v_min_u16_e32 v5, 15, v17
	s_addc_u32 s67, s63, 0
	v_lshl_add_u64 v[26:27], s[62:63], 0, v[2:3]
	s_movk_i32 s86, 0xc0
	v_lshlrev_b16_e32 v16, 3, v9
	v_lshlrev_b32_e32 v9, 10, v7
	v_lshlrev_b32_e32 v13, 10, v13
	v_lshlrev_b16_e32 v24, 3, v5
	v_lshlrev_b32_e32 v248, 10, v15
	s_movk_i32 s36, 0x2c0
	v_mov_b32_e32 v5, 0x80
	v_mov_b32_e32 v15, 0x3000
	v_cmp_gt_u32_e64 s[40:41], 26, v7
	v_cmp_gt_u32_e64 s[42:43], s42, v0
	s_add_u32 s68, s62, 0x5400400
	v_lshl_add_u64 v[26:27], v[26:27], 0, v[158:159]
	s_mov_b64 s[70:71], 0x17800400
	v_lshrrev_b32_e32 v175, 8, v0
	v_and_b32_e32 v177, 3, v188
	v_cmp_gt_u32_e64 s[2:3], v4, v156
	v_cmp_lt_u32_e64 s[4:5], v4, v156
	v_lshrrev_b32_e32 v244, 7, v0
	v_lshlrev_b32_e32 v245, 10, v188
	v_mov_b32_e32 v165, v3
	v_mov_b32_e32 v171, v3
	v_mov_b32_e32 v173, v3
	v_cmp_gt_u32_e64 s[36:37], s36, v0
	v_cmp_gt_u32_e64 s[38:39], s86, v0
	v_mul_u32_u24_e32 v249, 0xd0, v156
	v_mul_u32_u24_e32 v250, 0x110, v156
	v_cndmask_b32_e64 v174, v5, v15, s[40:41]
	s_mov_b32 s49, 0
	v_cndmask_b32_e64 v251, 0, v9, s[40:41]
	v_cndmask_b32_e64 v176, v5, v15, s[42:43]
	v_cndmask_b32_e64 v252, v11, v13, s[42:43]
	s_addc_u32 s69, s63, 0
	v_lshl_add_u64 v[180:181], v[26:27], 0, s[70:71]
	s_add_i32 s94, 0, 0x24000
	v_mov_b32_e32 v159, 0x358637bd
	v_lshlrev_b32_e32 v182, 1, v4
	v_lshlrev_b32_e32 v184, 1, v6
	v_lshlrev_b32_e32 v186, 1, v8
	v_lshlrev_b32_e32 v188, 1, v10
	v_lshlrev_b32_e32 v190, 1, v14
	v_lshlrev_b32_e32 v192, 1, v16
	v_lshlrev_b32_e32 v194, 1, v12
	v_lshlrev_b32_e32 v196, 1, v20
	v_lshlrev_b32_e32 v198, 1, v18
	v_lshlrev_b32_e32 v200, 1, v22
	s_mov_b64 s[70:71], 0x100
	v_lshlrev_b32_e32 v202, 1, v24
	s_mov_b64 s[72:73], 0x6000
	s_mov_b32 s95, 0x41000000
	s_branch .LBB0_593

.LBB0_611:
	s_cmp_lt_i32 s84, 0
	s_mov_b64 s[74:75], -1
	s_cbranch_scc0 .LBB0_623
	s_and_saveexec_b64 s[74:75], s[44:45]
	s_cbranch_execz .LBB0_622
	s_cmp_lg_u32 s98, 0
	s_cbranch_scc1 .LBB0_622
	s_add_u32 s76, s46, 0x100
	s_addc_u32 s77, s47, 0
	s_mov_b32 s85, 0x400001
	s_branch .LBB0_615

.LBB0_615:
	global_load_dword v2, v3, s[76:77] sc1
	s_mov_b64 s[78:79], -1
	s_waitcnt vmcnt(0)
	v_cmp_lt_u32_e32 vcc, 0x7f, v2
	s_cbranch_vccnz .LBB0_614
	s_sleep 2
	global_load_dword v2, v3, s[76:77] sc1
	s_waitcnt vmcnt(0)
	v_cmp_gt_u32_e32 vcc, 0x80, v2
	s_cbranch_vccz .LBB0_614
	s_sleep 2
	global_load_dword v2, v3, s[76:77] sc1
	s_waitcnt vmcnt(0)
	v_cmp_gt_u32_e32 vcc, 0x80, v2
	s_cbranch_vccz .LBB0_614
	s_sleep 2
	global_load_dword v2, v3, s[76:77] sc1
	s_waitcnt vmcnt(0)
	v_cmp_gt_u32_e32 vcc, 0x80, v2
	s_cbranch_vccz .LBB0_614
	s_sleep 2
	global_load_dword v2, v3, s[76:77] sc1
	s_waitcnt vmcnt(0)
	v_cmp_gt_u32_e32 vcc, 0x80, v2
	s_cbranch_vccz .LBB0_614
	s_add_i32 s85, s85, -5
	s_cmp_eq_u32 s85, 0
	s_cselect_b64 s[78:79], -1, 0
	s_sleep 2
	s_branch .LBB0_614
.LBB0_621:
	buffer_inv sc1
	s_waitcnt vmcnt(0)
	s_mov_b32 s98, 1

	.amdhsa_kernel _Z14fwd_megakernel6Params
		.amdhsa_group_segment_fixed_size 0
		.amdhsa_private_segment_fixed_size 0
		.amdhsa_kernarg_size 392
		.amdhsa_user_sgpr_count 2
		.amdhsa_user_sgpr_dispatch_ptr 0
		.amdhsa_user_sgpr_queue_ptr 0
		.amdhsa_user_sgpr_kernarg_segment_ptr 1
		.amdhsa_user_sgpr_dispatch_id 0
		.amdhsa_user_sgpr_kernarg_preload_length 0
		.amdhsa_user_sgpr_kernarg_preload_offset 0
		.amdhsa_user_sgpr_private_segment_size 0
		.amdhsa_uses_dynamic_stack 0
		.amdhsa_enable_private_segment 0
		.amdhsa_system_sgpr_workgroup_id_x 1
		.amdhsa_system_sgpr_workgroup_id_y 0
		.amdhsa_system_sgpr_workgroup_id_z 0
		.amdhsa_system_sgpr_workgroup_info 0
		.amdhsa_system_vgpr_workitem_id 0
		.amdhsa_next_free_vgpr 255
		.amdhsa_next_free_sgpr 99
		.amdhsa_accum_offset 256
		.amdhsa_reserve_vcc 1
		.amdhsa_float_round_mode_32 0
		.amdhsa_float_round_mode_16_64 0
		.amdhsa_float_denorm_mode_32 3
		.amdhsa_float_denorm_mode_16_64 3
		.amdhsa_dx10_clamp 1
		.amdhsa_ieee_mode 1
		.amdhsa_fp16_overflow 0
		.amdhsa_tg_split 0
		.amdhsa_exception_fp_ieee_invalid_op 0
		.amdhsa_exception_fp_denorm_src 0
		.amdhsa_exception_fp_ieee_div_zero 0
		.amdhsa_exception_fp_ieee_overflow 0
		.amdhsa_exception_fp_ieee_underflow 0
		.amdhsa_exception_fp_ieee_inexact 0
		.amdhsa_exception_int_div_zero 0
	.end_amdhsa_kernel

amdhsa.kernels:
  - .agpr_count:     0
    .args:
      - .offset:         0
        .size:           136
        .value_kind:     by_value
      - .offset:         136
        .size:           4
        .value_kind:     hidden_block_count_x
      - .offset:         140
        .size:           4
        .value_kind:     hidden_block_count_y
      - .offset:         144
        .size:           4
        .value_kind:     hidden_block_count_z
      - .offset:         148
        .size:           2
        .value_kind:     hidden_group_size_x
      - .offset:         150
        .size:           2
        .value_kind:     hidden_group_size_y
      - .offset:         152
        .size:           2
        .value_kind:     hidden_group_size_z
      - .offset:         154
        .size:           2
        .value_kind:     hidden_remainder_x
      - .offset:         156
        .size:           2
        .value_kind:     hidden_remainder_y
      - .offset:         158
        .size:           2
        .value_kind:     hidden_remainder_z
      - .offset:         176
        .size:           8
        .value_kind:     hidden_global_offset_x
      - .offset:         184
        .size:           8
        .value_kind:     hidden_global_offset_y
      - .offset:         192
        .size:           8
        .value_kind:     hidden_global_offset_z
      - .offset:         200
        .size:           2
        .value_kind:     hidden_grid_dims
      - .offset:         256
        .size:           4
        .value_kind:     hidden_dynamic_lds_size
    .group_segment_fixed_size: 0
    .kernarg_segment_align: 8
    .kernarg_segment_size: 392
    .language:       OpenCL C
    .language_version:
      - 2
      - 0
    .max_flat_workgroup_size: 512
    .name:           _Z14fwd_megakernel6Params
    .private_segment_fixed_size: 0
    .sgpr_count:     105
    .sgpr_spill_count: 16
    .symbol:         _Z14fwd_megakernel6Params.kd
    .uniform_work_group_size: 1
    .uses_dynamic_stack: false
    .vgpr_count:     255
    .vgpr_spill_count: 0
    .wavefront_size: 64
